# v1 plus one static s_setprio 1 for waves 4-7 during the attention phase
# speedup vs baseline: 1.0006x; 1.0006x over previous
; __global__ void __launch_bounds__(NTHR, 2) fwd_megakernel(Args args_unused) {
;     ...
;     {
;         PH_COMMON
;         const float d1 = wave_sum(A->in[2][lane] * A->in[3][lane]), d2 = wave_sum(A->in[4][lane] * A->in[5][lane]);
;         const float lam = __uint_as_float(__builtin_amdgcn_readfirstlane(__float_as_uint(__expf(d1) - __expf(d2) + 0.2f)));
;     ...
;         for (int w = vcu; w < 256; w += G) {
;             const int bhd = w >> 3, s = w & 7, b = bhd >> 3, hd = bhd & 7;
;             for (int j = 0; j < 4; ++j) { const int qb = (j == 0) ? s : (j == 1) ? 15 - s : (j == 2) ? 16 + s : 31 - s;
; #pragma unroll 1
;                 for (int cmap = 0; cmap < 2; ++cmap) { const int hh = 2 * hd + cmap, bh = b * 16 + hh;
;                     const float kmax = 1.01f * sqrtf(__uint_as_float(__builtin_amdgcn_readfirstlane(__hip_atomic_load((unsigned*)(ws + WS_KMAX) + 2 * bh, __ATOMIC_RELAXED, __HIP_MEMORY_SCOPE_AGENT)))
;                                                    + __uint_as_float(__builtin_amdgcn_readfirstlane(__hip_atomic_load((unsigned*)(ws + WS_KMAX) + 2 * bh + 1, __ATOMIC_RELAXED, __HIP_MEMORY_SCOPE_AGENT))));
;                     attn_body::attn_unit<8>(b, hh, qb, ws, (char*)lds_raw, kmax, cmap, lam); } }
.LBB0_293:
	v_readfirstlane_b32 s101, v230
	s_nop 3
	s_cmp_ge_u32 s101, 0x100
	s_cbranch_scc0 .Lattn_prio_done
	s_setprio 1

; __device__ __forceinline__ unsigned xb_add(unsigned* p, unsigned v) { return __hip_atomic_fetch_add(p, v, __ATOMIC_RELAXED, __HIP_MEMORY_SCOPE_AGENT); }
; __device__ __forceinline__ void xcd_barrier(const XcdBarrier& b) {
;     asm volatile("s_waitcnt vmcnt(0)" ::: "memory");
;     __syncthreads();
;     if (threadIdx.x == 0) {
;         unsigned* bar = b.bar;
;         __builtin_amdgcn_s_waitcnt(0);
;         unsigned nloc = b.st[0], nx = b.st[1];
;         if (nloc == 0u) { xcd_barrier_complete(bar, b.x, nloc, nx); b.st[0] = nloc; b.st[1] = nx; }
;         const unsigned old = xb_add(&bar[XB_XSUB(b.x)], 1u);
;         const unsigned gen = old / nloc;
;         if (old + 1u == (gen + 1u) * nloc) {
;             __builtin_amdgcn_fence(__ATOMIC_RELEASE, "agent");
;             asm volatile("s_waitcnt vmcnt(0)" ::: "memory");
.LBB0_373:
	s_setprio 0
	s_waitcnt vmcnt(0)
	s_waitcnt lgkmcnt(0)
	s_barrier
	s_mov_b64 s[4:5], exec
	v_readlane_b32 s6, v254, 5
	v_readlane_b32 s7, v254, 6
	v_readlane_b32 s28, v254, 1
	s_and_b64 s[6:7], s[4:5], s[6:7]
	v_readlane_b32 s29, v254, 2
	s_mov_b64 exec, s[6:7]
	s_cbranch_execz .LBB0_425
	s_add_i32 s1, 0, 0x20000
	v_mov_b32_e32 v0, s1
	s_waitcnt vmcnt(0) expcnt(0) lgkmcnt(0)
	ds_read_b32 v2, v0
	s_add_i32 s1, 0, 0x20004
	v_mov_b32_e32 v0, s1
	ds_read_b32 v0, v0
	s_waitcnt lgkmcnt(1)
	v_cmp_ne_u32_e32 vcc, 0, v2
	s_cbranch_vccnz .LBB0_389
	s_add_u32 s6, s44, 0x1000
	s_addc_u32 s7, s45, 0
	s_add_u32 s8, s44, 0x1100
	s_addc_u32 s9, s45, 0
	s_add_u32 s10, s44, 0x1200
	v_readlane_b32 s1, v254, 0
	s_addc_u32 s11, s45, 0
	s_mul_i32 s1, s41, s1
	s_add_u32 s12, s44, 0x1300
	s_mul_i32 s1, s1, s40
	s_addc_u32 s13, s45, 0
	s_mov_b32 s3, 1
	v_mov_b32_e32 v16, 0
	s_branch .LBB0_377
